# v12
# speedup vs baseline: 1.0008x; 1.0008x over previous
; __device__ __forceinline__ u32x2 pk4(float a, float b, float c, float d) { return u32x2{cvtpk(a, b), cvtpk(c, d)}; }
; template <int EPI>
; __device__ __forceinline__ void gemm_tile(const Params& p, const u16* __restrict__ A, int lda, const u16* __restrict__ Bt, int ldb,
;                                           int K, int brow, int bcol, bool prefetched, int nbrow, int nbcol, char* shm) {
;     ...
;     } else if constexpr (EPI == EPI_WO) {
;       u16* xb = (u16*)(p.ws + OFF_XB); float* ssq = ssqb + 3 * T_TOK;
; #pragma unroll
;       for (int m = 0; m < 8; ++m) {
;         const int row = rbase + m * 16; float s = 0.f; u32x2 g[4];
;         const float* xr = (row < TP ? p.xp + (long)row * DM : p.xs + (long)(row - TP) * DM) + col0 + cq4;
; #pragma unroll
;         for (int n = 0; n < 4; ++n) {
;           float4 v = *(const float4*)(xr + n * 16);
;           v.x += acc[m][n][0]; v.y += acc[m][n][1]; v.z += acc[m][n][2]; v.w += acc[m][n][3];
;           s += v.x * v.x + v.y * v.y + v.z * v.z + v.w * v.w;
;           *(float4*)(p.out + (long)row * DM + col0 + cq4 + n * 16) = v; g[n] = pk4(v.x, v.y, v.z, v.w);
;         }
;         st_row64(xb + (long)row * DM + col0, fq, g[0], g[1], g[2], g[3]);
;         s = red4q(s); if (fq == 0) unsafeAtomicAdd(&ssq[row], s);
;       }
.LBB0_420:
	s_or_b64 exec, exec, s[6:7]
	v_lshl_or_b32 v146, v186, 6, s18
	v_ashrrev_i32_e32 v147, 31, v146
	v_and_b32_e32 v134, 12, v185
	v_lshlrev_b64 v[128:129], 2, v[146:147]
	v_lshl_add_u64 v[132:133], v[132:133], 0, v[128:129]
	v_lshlrev_b32_e32 v172, 2, v134
	v_lshl_add_u64 v[142:143], v[132:133], 0, v[172:173]
	global_load_dwordx4 v[152:155], v[142:143], off
	global_load_dwordx4 v[156:159], v[142:143], off offset:64
	global_load_dwordx4 v[160:163], v[142:143], off offset:128
	global_load_dwordx4 v[164:167], v[142:143], off offset:192
	s_mov_b64 s[98:99], 0x10000
	v_lshl_add_u64 v[228:229], v[142:143], 0, s[98:99]
	global_load_dwordx4 v[168:171], v[228:229], off
	global_load_dwordx4 v[216:219], v[228:229], off offset:64
	global_load_dwordx4 v[220:223], v[228:229], off offset:128
	global_load_dwordx4 v[224:227], v[228:229], off offset:192
	v_readlane_b32 s72, v255, 0
	v_readlane_b32 s73, v255, 1
	v_cmp_gt_u32_e32 vcc, 16, v184
	v_readlane_b32 s74, v255, 2
	v_lshl_add_u64 v[130:131], s[72:73], 0, v[130:131]
	v_lshl_add_u64 v[130:131], v[130:131], 0, v[128:129]
	v_lshl_add_u64 v[148:149], v[130:131], 0, v[172:173]
	v_readlane_b32 s75, v255, 3
	v_readlane_b32 s76, v255, 4
	v_readlane_b32 s77, v255, 5
	v_readlane_b32 s78, v255, 6
	v_readlane_b32 s79, v255, 7
	v_readlane_b32 s80, v255, 8
	v_readlane_b32 s81, v255, 9
	v_readlane_b32 s82, v255, 10
	v_readlane_b32 s83, v255, 11
	v_readlane_b32 s84, v255, 12
	v_readlane_b32 s85, v255, 13
	v_readlane_b32 s86, v255, 14
	v_readlane_b32 s87, v255, 15
	s_waitcnt vmcnt(4)
	v_mov_b64_e32 v[132:133], v[152:153]
	v_mov_b64_e32 v[134:135], v[154:155]
	v_pk_add_f32 v[130:131], v[124:125], v[132:133]
	v_pk_add_f32 v[132:133], v[126:127], v[134:135]
	global_store_dwordx4 v[148:149], v[130:133], off
	v_mov_b64_e32 v[124:125], v[156:157]
	v_mov_b64_e32 v[126:127], v[158:159]
	v_pk_add_f32 v[134:135], v[120:121], v[124:125]
	v_pk_add_f32 v[136:137], v[122:123], v[126:127]
	global_store_dwordx4 v[148:149], v[134:137], off offset:64
	v_mov_b64_e32 v[120:121], v[160:161]
	v_mov_b64_e32 v[122:123], v[162:163]
	v_xor_b32_e32 v124, 16, v182
	v_xor_b32_e32 v125, 32, v182
	v_pk_add_f32 v[138:139], v[116:117], v[120:121]
	v_pk_add_f32 v[140:141], v[118:119], v[122:123]
	global_store_dwordx4 v[148:149], v[138:141], off offset:128
	v_mov_b64_e32 v[142:143], v[164:165]
	v_mov_b64_e32 v[144:145], v[166:167]
	v_and_b32_e32 v120, 64, v182
	v_add_u32_e32 v126, 64, v120
	v_cmp_lt_i32_e64 s[6:7], v124, v126
	v_and_b32_e32 v116, 16, v183
	v_lshlrev_b64 v[122:123], 11, v[174:175]
	v_cndmask_b32_e64 v124, v182, v124, s[6:7]
	v_cmp_lt_i32_e64 s[6:7], v125, v126
	v_lshl_add_u64 v[120:121], v[146:147], 1, s[36:37]
	v_mov_b32_e32 v117, v173
	v_cndmask_b32_e64 v126, v182, v125, s[6:7]
	v_lshlrev_b32_e32 v116, 1, v116
	v_lshlrev_b32_e32 v125, 2, v124
	v_lshlrev_b32_e32 v124, 2, v126
	v_lshl_add_u64 v[122:123], v[120:121], 0, v[122:123]
	v_pk_mul_f32 v[126:127], v[130:131], v[130:131]
	v_and_b32_e32 v118, 8, v185
	v_lshl_add_u64 v[122:123], v[122:123], 0, v[116:117]
	v_pk_mul_f32 v[146:147], v[132:133], v[132:133]
	v_add_f32_e32 v117, v126, v127
	v_mov_b32_e32 v119, v173
	v_lshlrev_b32_e32 v118, 1, v118
	v_add_f32_e32 v117, v146, v117
	v_pk_mul_f32 v[126:127], v[134:135], v[134:135]
	v_lshl_add_u64 v[122:123], v[122:123], 0, v[118:119]
	v_add_f32_e32 v117, v147, v117
	v_pk_mul_f32 v[146:147], v[136:137], v[136:137]
	v_add_f32_e32 v119, v126, v127
	v_add_f32_e32 v119, v146, v119
	v_add_f32_e32 v119, v147, v119
	v_pk_mul_f32 v[126:127], v[138:139], v[138:139]
	v_cvt_pk_bf16_f32 v130, v130, v131
	v_cvt_pk_bf16_f32 v131, v132, v133
	v_cvt_pk_bf16_f32 v133, v136, v137
	v_add_f32_e32 v117, v117, v119
	v_pk_mul_f32 v[136:137], v[140:141], v[140:141]
	v_add_f32_e32 v119, v126, v127
	v_add_f32_e32 v119, v136, v119
	v_add_f32_e32 v119, v137, v119
	v_add_f32_e32 v117, v117, v119
	v_cvt_pk_bf16_f32 v132, v134, v135
	v_cvt_pk_bf16_f32 v134, v138, v139
	v_cvt_pk_bf16_f32 v135, v140, v141
	v_permlane16_swap_b32_e32 v130, v132
	v_permlane16_swap_b32_e32 v131, v133
	v_pk_add_f32 v[112:113], v[112:113], v[142:143]
	v_pk_add_f32 v[114:115], v[114:115], v[144:145]
	v_pk_mul_f32 v[126:127], v[112:113], v[112:113]
	v_pk_mul_f32 v[136:137], v[114:115], v[114:115]
	v_add_f32_e32 v119, v126, v127
	v_add_f32_e32 v119, v136, v119
	v_add_f32_e32 v119, v137, v119
	v_add_f32_e32 v117, v117, v119
	ds_bpermute_b32 v119, v125, v117
	global_store_dwordx4 v[148:149], v[112:115], off offset:192
	v_cvt_pk_bf16_f32 v136, v112, v113
	v_cvt_pk_bf16_f32 v137, v114, v115
	s_nop 0
	v_permlane16_swap_b32_e32 v134, v136
	s_waitcnt lgkmcnt(0)
	v_add_f32_e32 v112, v117, v119
	ds_bpermute_b32 v113, v124, v112
	v_permlane16_swap_b32_e32 v135, v137
	global_store_dwordx4 v[122:123], v[130:133], off
	global_store_dwordx4 v[122:123], v[134:137], off offset:64
	s_and_saveexec_b64 s[6:7], vcc
	s_cbranch_execz .LBB0_422
	s_waitcnt lgkmcnt(0)
	v_add_f32_e32 v114, v112, v113
	v_lshl_add_u64 v[112:113], v[174:175], 2, s[12:13]
	global_atomic_add_f32 v[112:113], v114, off

; __device__ __forceinline__ u32x2 pk4(float a, float b, float c, float d) { return u32x2{cvtpk(a, b), cvtpk(c, d)}; }
; template <int EPI>
; __device__ __forceinline__ void gemm_tile(const Params& p, const u16* __restrict__ A, int lda, const u16* __restrict__ Bt, int ldb,
;                                           int K, int brow, int bcol, bool prefetched, int nbrow, int nbcol, char* shm) {
;     ...
;     } else if constexpr (EPI == EPI_WO) {
;       u16* xb = (u16*)(p.ws + OFF_XB); float* ssq = ssqb + 3 * T_TOK;
; #pragma unroll
;       for (int m = 0; m < 8; ++m) {
;         const int row = rbase + m * 16; float s = 0.f; u32x2 g[4];
;         const float* xr = (row < TP ? p.xp + (long)row * DM : p.xs + (long)(row - TP) * DM) + col0 + cq4;
; #pragma unroll
;         for (int n = 0; n < 4; ++n) {
;           float4 v = *(const float4*)(xr + n * 16);
;           v.x += acc[m][n][0]; v.y += acc[m][n][1]; v.z += acc[m][n][2]; v.w += acc[m][n][3];
;           s += v.x * v.x + v.y * v.y + v.z * v.z + v.w * v.w;
;           *(float4*)(p.out + (long)row * DM + col0 + cq4 + n * 16) = v; g[n] = pk4(v.x, v.y, v.z, v.w);
;         }
;         st_row64(xb + (long)row * DM + col0, fq, g[0], g[1], g[2], g[3]);
;         s = red4q(s); if (fq == 0) unsafeAtomicAdd(&ssq[row], s);
;       }
.LBB0_426:
	s_or_b64 exec, exec, s[6:7]
	v_lshl_add_u64 v[122:123], v[122:123], 0, v[128:129]
	v_lshl_add_u64 v[122:123], v[122:123], 0, v[172:173]
	v_lshl_add_u64 v[228:229], v[228:229], 0, s[98:99]
	global_load_dwordx4 v[152:155], v[228:229], off
	global_load_dwordx4 v[156:159], v[228:229], off offset:64
	global_load_dwordx4 v[160:163], v[228:229], off offset:128
	global_load_dwordx4 v[164:167], v[228:229], off offset:192
	v_readlane_b32 s72, v255, 0
	v_readlane_b32 s73, v255, 1
	v_mov_b32_e32 v117, v173
	v_mov_b32_e32 v119, v173
	v_lshl_add_u64 v[114:115], s[72:73], 0, v[114:115]
	v_lshl_add_u64 v[114:115], v[114:115], 0, v[128:129]
	v_lshl_add_u64 v[114:115], v[114:115], 0, v[172:173]
	v_readlane_b32 s74, v255, 2
	v_readlane_b32 s75, v255, 3
	v_readlane_b32 s76, v255, 4
	v_readlane_b32 s77, v255, 5
	v_readlane_b32 s78, v255, 6
	v_readlane_b32 s79, v255, 7
	v_readlane_b32 s80, v255, 8
	v_readlane_b32 s81, v255, 9
	v_readlane_b32 s82, v255, 10
	v_readlane_b32 s83, v255, 11
	v_readlane_b32 s84, v255, 12
	v_readlane_b32 s85, v255, 13
	v_readlane_b32 s86, v255, 14
	v_readlane_b32 s87, v255, 15
	s_waitcnt vmcnt(10)
	v_mov_b64_e32 v[130:131], v[168:169]
	v_mov_b64_e32 v[132:133], v[170:171]
	v_pk_add_f32 v[108:109], v[108:109], v[130:131]
	v_pk_add_f32 v[110:111], v[110:111], v[132:133]
	global_store_dwordx4 v[114:115], v[108:111], off
	v_mov_b64_e32 v[130:131], v[216:217]
	v_mov_b64_e32 v[132:133], v[218:219]
	v_pk_mul_f32 v[126:127], v[108:109], v[108:109]
	v_pk_mul_f32 v[134:135], v[110:111], v[110:111]
	v_cvt_pk_bf16_f32 v108, v108, v109
	v_cvt_pk_bf16_f32 v109, v110, v111
	v_add_f32_e32 v110, v126, v127
	v_add_f32_e32 v110, v134, v110
	v_pk_add_f32 v[104:105], v[104:105], v[130:131]
	v_pk_add_f32 v[106:107], v[106:107], v[132:133]
	global_store_dwordx4 v[114:115], v[104:107], off offset:64
	v_mov_b64_e32 v[130:131], v[220:221]
	v_mov_b64_e32 v[132:133], v[222:223]
	v_pk_mul_f32 v[126:127], v[104:105], v[104:105]
	v_cvt_pk_bf16_f32 v111, v106, v107
	s_nop 1
	v_permlane16_swap_b32_e32 v109, v111
	v_pk_add_f32 v[100:101], v[100:101], v[130:131]
	v_pk_add_f32 v[102:103], v[102:103], v[132:133]
	global_store_dwordx4 v[114:115], v[100:103], off offset:128
	v_mov_b64_e32 v[130:131], v[224:225]
	v_mov_b64_e32 v[132:133], v[226:227]
	v_lshlrev_b64 v[122:123], 11, v[112:113]
	v_lshl_add_u64 v[122:123], v[120:121], 0, v[122:123]
	v_lshl_add_u64 v[122:123], v[122:123], 0, v[116:117]
	v_add_f32_e32 v117, v135, v110
	v_pk_mul_f32 v[134:135], v[106:107], v[106:107]
	v_cvt_pk_bf16_f32 v110, v104, v105
	v_add_f32_e32 v104, v126, v127
	v_add_f32_e32 v104, v134, v104
	v_add_f32_e32 v104, v135, v104
	v_add_f32_e32 v117, v117, v104
	v_pk_mul_f32 v[104:105], v[100:101], v[100:101]
	v_pk_mul_f32 v[106:107], v[102:103], v[102:103]
	v_cvt_pk_bf16_f32 v100, v100, v101
	v_cvt_pk_bf16_f32 v101, v102, v103
	v_add_f32_e32 v102, v104, v105
	v_add_f32_e32 v102, v106, v102
	v_add_f32_e32 v102, v107, v102
	v_add_f32_e32 v106, v117, v102
	v_lshl_add_u64 v[122:123], v[122:123], 0, v[118:119]
	v_permlane16_swap_b32_e32 v108, v110
	v_pk_add_f32 v[96:97], v[96:97], v[130:131]
	v_pk_add_f32 v[98:99], v[98:99], v[132:133]
	v_pk_mul_f32 v[102:103], v[96:97], v[96:97]
	v_pk_mul_f32 v[104:105], v[98:99], v[98:99]
	v_add_f32_e32 v102, v102, v103
	v_add_f32_e32 v102, v104, v102
	v_add_f32_e32 v102, v105, v102
	v_add_f32_e32 v104, v106, v102
	ds_bpermute_b32 v105, v125, v104
	global_store_dwordx4 v[114:115], v[96:99], off offset:192
	v_cvt_pk_bf16_f32 v102, v96, v97
	v_cvt_pk_bf16_f32 v103, v98, v99
	s_nop 0
	v_permlane16_swap_b32_e32 v100, v102
	s_waitcnt lgkmcnt(0)
	v_add_f32_e32 v96, v104, v105
	ds_bpermute_b32 v97, v124, v96
	v_permlane16_swap_b32_e32 v101, v103
	global_store_dwordx4 v[122:123], v[108:111], off
	global_store_dwordx4 v[122:123], v[100:103], off offset:64
	s_and_saveexec_b64 s[6:7], vcc
	s_cbranch_execz .LBB0_428
	s_waitcnt lgkmcnt(0)
	v_add_f32_e32 v98, v96, v97
	v_lshl_add_u64 v[96:97], v[112:113], 2, s[12:13]
	global_atomic_add_f32 v[96:97], v98, off

; __device__ __forceinline__ u32x2 pk4(float a, float b, float c, float d) { return u32x2{cvtpk(a, b), cvtpk(c, d)}; }
; template <int EPI>
; __device__ __forceinline__ void gemm_tile(const Params& p, const u16* __restrict__ A, int lda, const u16* __restrict__ Bt, int ldb,
;                                           int K, int brow, int bcol, bool prefetched, int nbrow, int nbcol, char* shm) {
;     ...
;     } else if constexpr (EPI == EPI_WO) {
;       u16* xb = (u16*)(p.ws + OFF_XB); float* ssq = ssqb + 3 * T_TOK;
; #pragma unroll
;       for (int m = 0; m < 8; ++m) {
;         const int row = rbase + m * 16; float s = 0.f; u32x2 g[4];
;         const float* xr = (row < TP ? p.xp + (long)row * DM : p.xs + (long)(row - TP) * DM) + col0 + cq4;
; #pragma unroll
;         for (int n = 0; n < 4; ++n) {
;           float4 v = *(const float4*)(xr + n * 16);
;           v.x += acc[m][n][0]; v.y += acc[m][n][1]; v.z += acc[m][n][2]; v.w += acc[m][n][3];
;           s += v.x * v.x + v.y * v.y + v.z * v.z + v.w * v.w;
;           *(float4*)(p.out + (long)row * DM + col0 + cq4 + n * 16) = v; g[n] = pk4(v.x, v.y, v.z, v.w);
;         }
;         st_row64(xb + (long)row * DM + col0, fq, g[0], g[1], g[2], g[3]);
;         s = red4q(s); if (fq == 0) unsafeAtomicAdd(&ssq[row], s);
;       }
.LBB0_432:
	s_or_b64 exec, exec, s[6:7]
	v_lshl_add_u64 v[100:101], v[100:101], 0, v[128:129]
	v_lshl_add_u64 v[104:105], v[100:101], 0, v[172:173]
	v_lshl_add_u64 v[228:229], v[228:229], 0, s[98:99]
	global_load_dwordx4 v[168:171], v[228:229], off
	global_load_dwordx4 v[216:219], v[228:229], off offset:64
	global_load_dwordx4 v[220:223], v[228:229], off offset:128
	global_load_dwordx4 v[224:227], v[228:229], off offset:192
	v_readlane_b32 s72, v255, 0
	v_readlane_b32 s73, v255, 1
	v_mov_b32_e32 v117, v173
	v_mov_b32_e32 v119, v173
	v_lshl_add_u64 v[98:99], s[72:73], 0, v[98:99]
	v_lshl_add_u64 v[98:99], v[98:99], 0, v[128:129]
	v_lshl_add_u64 v[106:107], v[98:99], 0, v[172:173]
	v_readlane_b32 s74, v255, 2
	v_readlane_b32 s75, v255, 3
	v_readlane_b32 s76, v255, 4
	v_readlane_b32 s77, v255, 5
	v_readlane_b32 s78, v255, 6
	v_readlane_b32 s79, v255, 7
	v_readlane_b32 s80, v255, 8
	v_readlane_b32 s81, v255, 9
	v_readlane_b32 s82, v255, 10
	v_readlane_b32 s83, v255, 11
	v_readlane_b32 s84, v255, 12
	v_readlane_b32 s85, v255, 13
	v_readlane_b32 s86, v255, 14
	v_readlane_b32 s87, v255, 15
	s_waitcnt vmcnt(10)
	v_mov_b64_e32 v[100:101], v[152:153]
	v_mov_b64_e32 v[102:103], v[154:155]
	v_pk_add_f32 v[92:93], v[92:93], v[100:101]
	v_pk_add_f32 v[94:95], v[94:95], v[102:103]
	global_store_dwordx4 v[106:107], v[92:95], off
	v_mov_b64_e32 v[98:99], v[156:157]
	v_mov_b64_e32 v[100:101], v[158:159]
	v_pk_mul_f32 v[108:109], v[94:95], v[94:95]
	v_lshlrev_b64 v[102:103], 11, v[96:97]
	v_lshl_add_u64 v[102:103], v[120:121], 0, v[102:103]
	v_lshl_add_u64 v[102:103], v[102:103], 0, v[116:117]
	v_lshl_add_u64 v[102:103], v[102:103], 0, v[118:119]
	v_pk_add_f32 v[88:89], v[88:89], v[98:99]
	v_pk_add_f32 v[90:91], v[90:91], v[100:101]
	global_store_dwordx4 v[106:107], v[88:91], off offset:64
	v_mov_b64_e32 v[98:99], v[160:161]
	v_mov_b64_e32 v[100:101], v[162:163]
	v_pk_add_f32 v[84:85], v[84:85], v[98:99]
	v_pk_add_f32 v[86:87], v[86:87], v[100:101]
	global_store_dwordx4 v[106:107], v[84:87], off offset:128
	v_mov_b64_e32 v[98:99], v[164:165]
	v_mov_b64_e32 v[100:101], v[166:167]
	v_pk_mul_f32 v[104:105], v[92:93], v[92:93]
	v_cvt_pk_bf16_f32 v92, v92, v93
	v_cvt_pk_bf16_f32 v93, v94, v95
	v_add_f32_e32 v94, v104, v105
	v_add_f32_e32 v94, v108, v94
	v_pk_mul_f32 v[104:105], v[88:89], v[88:89]
	v_add_f32_e32 v110, v109, v94
	v_pk_mul_f32 v[108:109], v[90:91], v[90:91]
	v_cvt_pk_bf16_f32 v94, v88, v89
	v_add_f32_e32 v88, v104, v105
	v_add_f32_e32 v88, v108, v88
	v_add_f32_e32 v88, v109, v88
	v_add_f32_e32 v104, v110, v88
	v_pk_mul_f32 v[88:89], v[84:85], v[84:85]
	v_cvt_pk_bf16_f32 v95, v90, v91
	v_pk_mul_f32 v[90:91], v[86:87], v[86:87]
	v_cvt_pk_bf16_f32 v84, v84, v85
	v_cvt_pk_bf16_f32 v85, v86, v87
	v_add_f32_e32 v86, v88, v89
	v_add_f32_e32 v86, v90, v86
	v_add_f32_e32 v86, v91, v86
	v_add_f32_e32 v90, v104, v86
	v_permlane16_swap_b32_e32 v92, v94
	v_permlane16_swap_b32_e32 v93, v95
	v_pk_add_f32 v[80:81], v[80:81], v[98:99]
	v_pk_add_f32 v[82:83], v[82:83], v[100:101]
	v_pk_mul_f32 v[86:87], v[80:81], v[80:81]
	v_pk_mul_f32 v[88:89], v[82:83], v[82:83]
	v_add_f32_e32 v86, v86, v87
	v_add_f32_e32 v86, v88, v86
	v_add_f32_e32 v86, v89, v86
	v_add_f32_e32 v88, v90, v86
	ds_bpermute_b32 v89, v125, v88
	global_store_dwordx4 v[106:107], v[80:83], off offset:192
	v_cvt_pk_bf16_f32 v86, v80, v81
	v_cvt_pk_bf16_f32 v87, v82, v83
	s_nop 0
	v_permlane16_swap_b32_e32 v84, v86
	s_waitcnt lgkmcnt(0)
	v_add_f32_e32 v80, v88, v89
	ds_bpermute_b32 v81, v124, v80
	v_permlane16_swap_b32_e32 v85, v87
	global_store_dwordx4 v[102:103], v[92:95], off
	global_store_dwordx4 v[102:103], v[84:87], off offset:64
	s_and_saveexec_b64 s[6:7], vcc
	s_cbranch_execz .LBB0_434
	s_waitcnt lgkmcnt(0)
	v_add_f32_e32 v82, v80, v81
	v_lshl_add_u64 v[80:81], v[96:97], 2, s[12:13]
	global_atomic_add_f32 v[80:81], v82, off

; __device__ __forceinline__ u32x2 pk4(float a, float b, float c, float d) { return u32x2{cvtpk(a, b), cvtpk(c, d)}; }
; template <int EPI>
; __device__ __forceinline__ void gemm_tile(const Params& p, const u16* __restrict__ A, int lda, const u16* __restrict__ Bt, int ldb,
;                                           int K, int brow, int bcol, bool prefetched, int nbrow, int nbcol, char* shm) {
;     ...
;       for (int m = 0; m < 8; ++m) {
;         const int row = rbase + m * 16; float s = 0.f; u32x2 g[4];
;         const float* xr = (row < TP ? p.xp + (long)row * DM : p.xs + (long)(row - TP) * DM) + col0 + cq4;
; #pragma unroll
;         for (int n = 0; n < 4; ++n) {
;           float4 v = *(const float4*)(xr + n * 16);
;           v.x += acc[m][n][0]; v.y += acc[m][n][1]; v.z += acc[m][n][2]; v.w += acc[m][n][3];
;           s += v.x * v.x + v.y * v.y + v.z * v.z + v.w * v.w;
;           *(float4*)(p.out + (long)row * DM + col0 + cq4 + n * 16) = v; g[n] = pk4(v.x, v.y, v.z, v.w);
;         }
;         st_row64(xb + (long)row * DM + col0, fq, g[0], g[1], g[2], g[3]);
;         s = red4q(s); if (fq == 0) unsafeAtomicAdd(&ssq[row], s);
.LBB0_438:
	s_or_b64 exec, exec, s[6:7]
	v_lshl_add_u64 v[84:85], v[84:85], 0, v[128:129]
	v_lshl_add_u64 v[88:89], v[84:85], 0, v[172:173]
	v_lshl_add_u64 v[228:229], v[228:229], 0, s[98:99]
	global_load_dwordx4 v[152:155], v[228:229], off
	global_load_dwordx4 v[156:159], v[228:229], off offset:64
	global_load_dwordx4 v[160:163], v[228:229], off offset:128
	global_load_dwordx4 v[164:167], v[228:229], off offset:192
	v_readlane_b32 s72, v255, 0
	v_readlane_b32 s73, v255, 1
	v_mov_b32_e32 v117, v173
	v_mov_b32_e32 v119, v173
	v_lshl_add_u64 v[82:83], s[72:73], 0, v[82:83]
	v_lshl_add_u64 v[82:83], v[82:83], 0, v[128:129]
	v_lshl_add_u64 v[90:91], v[82:83], 0, v[172:173]
	v_readlane_b32 s74, v255, 2
	v_readlane_b32 s75, v255, 3
	v_readlane_b32 s76, v255, 4
	v_readlane_b32 s77, v255, 5
	v_readlane_b32 s78, v255, 6
	v_readlane_b32 s79, v255, 7
	v_readlane_b32 s80, v255, 8
	v_readlane_b32 s81, v255, 9
	v_readlane_b32 s82, v255, 10
	v_readlane_b32 s83, v255, 11
	v_readlane_b32 s84, v255, 12
	v_readlane_b32 s85, v255, 13
	v_readlane_b32 s86, v255, 14
	v_readlane_b32 s87, v255, 15
	s_waitcnt vmcnt(10)
	v_mov_b64_e32 v[84:85], v[168:169]
	v_mov_b64_e32 v[86:87], v[170:171]
	v_pk_add_f32 v[76:77], v[76:77], v[84:85]
	v_pk_add_f32 v[78:79], v[78:79], v[86:87]
	global_store_dwordx4 v[90:91], v[76:79], off
	v_mov_b64_e32 v[82:83], v[216:217]
	v_mov_b64_e32 v[84:85], v[218:219]
	v_pk_mul_f32 v[92:93], v[78:79], v[78:79]
	v_lshlrev_b64 v[86:87], 11, v[80:81]
	v_lshl_add_u64 v[86:87], v[120:121], 0, v[86:87]
	v_lshl_add_u64 v[86:87], v[86:87], 0, v[116:117]
	v_lshl_add_u64 v[86:87], v[86:87], 0, v[118:119]
	v_pk_add_f32 v[72:73], v[72:73], v[82:83]
	v_pk_add_f32 v[74:75], v[74:75], v[84:85]
	global_store_dwordx4 v[90:91], v[72:75], off offset:64
	v_mov_b64_e32 v[82:83], v[220:221]
	v_mov_b64_e32 v[84:85], v[222:223]
	v_pk_add_f32 v[68:69], v[68:69], v[82:83]
	v_pk_add_f32 v[70:71], v[70:71], v[84:85]
	global_store_dwordx4 v[90:91], v[68:71], off offset:128
	v_mov_b64_e32 v[82:83], v[224:225]
	v_mov_b64_e32 v[84:85], v[226:227]
	v_pk_mul_f32 v[88:89], v[76:77], v[76:77]
	v_cvt_pk_bf16_f32 v76, v76, v77
	v_cvt_pk_bf16_f32 v77, v78, v79
	v_add_f32_e32 v78, v88, v89
	v_add_f32_e32 v78, v92, v78
	v_pk_mul_f32 v[88:89], v[72:73], v[72:73]
	v_add_f32_e32 v94, v93, v78
	v_pk_mul_f32 v[92:93], v[74:75], v[74:75]
	v_cvt_pk_bf16_f32 v78, v72, v73
	v_add_f32_e32 v72, v88, v89
	v_add_f32_e32 v72, v92, v72
	v_add_f32_e32 v72, v93, v72
	v_add_f32_e32 v88, v94, v72
	v_pk_mul_f32 v[72:73], v[68:69], v[68:69]
	v_cvt_pk_bf16_f32 v79, v74, v75
	v_pk_mul_f32 v[74:75], v[70:71], v[70:71]
	v_cvt_pk_bf16_f32 v68, v68, v69
	v_cvt_pk_bf16_f32 v69, v70, v71
	v_add_f32_e32 v70, v72, v73
	v_add_f32_e32 v70, v74, v70
	v_add_f32_e32 v70, v75, v70
	v_add_f32_e32 v74, v88, v70
	v_permlane16_swap_b32_e32 v76, v78
	v_permlane16_swap_b32_e32 v77, v79
	v_pk_add_f32 v[64:65], v[64:65], v[82:83]
	v_pk_add_f32 v[66:67], v[66:67], v[84:85]
	v_pk_mul_f32 v[70:71], v[64:65], v[64:65]
	v_pk_mul_f32 v[72:73], v[66:67], v[66:67]
	v_add_f32_e32 v70, v70, v71
	v_add_f32_e32 v70, v72, v70
	v_add_f32_e32 v70, v73, v70
	v_add_f32_e32 v72, v74, v70
	ds_bpermute_b32 v73, v125, v72
	global_store_dwordx4 v[90:91], v[64:67], off offset:192
	v_cvt_pk_bf16_f32 v70, v64, v65
	v_cvt_pk_bf16_f32 v71, v66, v67
	s_nop 0
	v_permlane16_swap_b32_e32 v68, v70
	s_waitcnt lgkmcnt(0)
	v_add_f32_e32 v64, v72, v73
	ds_bpermute_b32 v65, v124, v64
	v_permlane16_swap_b32_e32 v69, v71
	global_store_dwordx4 v[86:87], v[76:79], off
	global_store_dwordx4 v[86:87], v[68:71], off offset:64
	s_and_saveexec_b64 s[6:7], vcc
	s_cbranch_execz .LBB0_440
	s_waitcnt lgkmcnt(0)
	v_add_f32_e32 v66, v64, v65
	v_lshl_add_u64 v[64:65], v[80:81], 2, s[12:13]
	global_atomic_add_f32 v[64:65], v66, off

; __device__ __forceinline__ u32x2 pk4(float a, float b, float c, float d) { return u32x2{cvtpk(a, b), cvtpk(c, d)}; }
; template <int EPI>
; __device__ __forceinline__ void gemm_tile(const Params& p, const u16* __restrict__ A, int lda, const u16* __restrict__ Bt, int ldb,
;                                           int K, int brow, int bcol, bool prefetched, int nbrow, int nbcol, char* shm) {
;     ...
;       for (int m = 0; m < 8; ++m) {
;         const int row = rbase + m * 16; float s = 0.f; u32x2 g[4];
;         const float* xr = (row < TP ? p.xp + (long)row * DM : p.xs + (long)(row - TP) * DM) + col0 + cq4;
; #pragma unroll
;         for (int n = 0; n < 4; ++n) {
;           float4 v = *(const float4*)(xr + n * 16);
;           v.x += acc[m][n][0]; v.y += acc[m][n][1]; v.z += acc[m][n][2]; v.w += acc[m][n][3];
;           s += v.x * v.x + v.y * v.y + v.z * v.z + v.w * v.w;
;           *(float4*)(p.out + (long)row * DM + col0 + cq4 + n * 16) = v; g[n] = pk4(v.x, v.y, v.z, v.w);
;         }
;         st_row64(xb + (long)row * DM + col0, fq, g[0], g[1], g[2], g[3]);
;         s = red4q(s); if (fq == 0) unsafeAtomicAdd(&ssq[row], s);
.LBB0_444:
	s_or_b64 exec, exec, s[6:7]
	v_lshl_add_u64 v[68:69], v[68:69], 0, v[128:129]
	v_lshl_add_u64 v[72:73], v[68:69], 0, v[172:173]
	v_lshl_add_u64 v[228:229], v[228:229], 0, s[98:99]
	global_load_dwordx4 v[168:171], v[228:229], off
	global_load_dwordx4 v[216:219], v[228:229], off offset:64
	global_load_dwordx4 v[220:223], v[228:229], off offset:128
	global_load_dwordx4 v[224:227], v[228:229], off offset:192
	v_readlane_b32 s72, v255, 0
	v_readlane_b32 s73, v255, 1
	v_mov_b32_e32 v117, v173
	v_mov_b32_e32 v119, v173
	v_lshl_add_u64 v[66:67], s[72:73], 0, v[66:67]
	v_lshl_add_u64 v[66:67], v[66:67], 0, v[128:129]
	v_lshl_add_u64 v[74:75], v[66:67], 0, v[172:173]
	v_readlane_b32 s74, v255, 2
	v_readlane_b32 s75, v255, 3
	v_readlane_b32 s76, v255, 4
	v_readlane_b32 s77, v255, 5
	v_readlane_b32 s78, v255, 6
	v_readlane_b32 s79, v255, 7
	v_readlane_b32 s80, v255, 8
	v_readlane_b32 s81, v255, 9
	v_readlane_b32 s82, v255, 10
	v_readlane_b32 s83, v255, 11
	v_readlane_b32 s84, v255, 12
	v_readlane_b32 s85, v255, 13
	v_readlane_b32 s86, v255, 14
	v_readlane_b32 s87, v255, 15
	s_waitcnt vmcnt(10)
	v_mov_b64_e32 v[68:69], v[152:153]
	v_mov_b64_e32 v[70:71], v[154:155]
	v_pk_add_f32 v[60:61], v[60:61], v[68:69]
	v_pk_add_f32 v[62:63], v[62:63], v[70:71]
	global_store_dwordx4 v[74:75], v[60:63], off
	v_mov_b64_e32 v[66:67], v[156:157]
	v_mov_b64_e32 v[68:69], v[158:159]
	v_pk_mul_f32 v[76:77], v[62:63], v[62:63]
	v_lshlrev_b64 v[70:71], 11, v[64:65]
	v_lshl_add_u64 v[70:71], v[120:121], 0, v[70:71]
	v_lshl_add_u64 v[70:71], v[70:71], 0, v[116:117]
	v_lshl_add_u64 v[70:71], v[70:71], 0, v[118:119]
	v_pk_add_f32 v[56:57], v[56:57], v[66:67]
	v_pk_add_f32 v[58:59], v[58:59], v[68:69]
	global_store_dwordx4 v[74:75], v[56:59], off offset:64
	v_mov_b64_e32 v[66:67], v[160:161]
	v_mov_b64_e32 v[68:69], v[162:163]
	v_pk_add_f32 v[52:53], v[52:53], v[66:67]
	v_pk_add_f32 v[54:55], v[54:55], v[68:69]
	global_store_dwordx4 v[74:75], v[52:55], off offset:128
	v_mov_b64_e32 v[66:67], v[164:165]
	v_mov_b64_e32 v[68:69], v[166:167]
	v_pk_mul_f32 v[72:73], v[60:61], v[60:61]
	v_cvt_pk_bf16_f32 v60, v60, v61
	v_cvt_pk_bf16_f32 v61, v62, v63
	v_add_f32_e32 v62, v72, v73
	v_add_f32_e32 v62, v76, v62
	v_pk_mul_f32 v[72:73], v[56:57], v[56:57]
	v_add_f32_e32 v78, v77, v62
	v_pk_mul_f32 v[76:77], v[58:59], v[58:59]
	v_cvt_pk_bf16_f32 v62, v56, v57
	v_add_f32_e32 v56, v72, v73
	v_add_f32_e32 v56, v76, v56
	v_add_f32_e32 v56, v77, v56
	v_add_f32_e32 v72, v78, v56
	v_pk_mul_f32 v[56:57], v[52:53], v[52:53]
	v_cvt_pk_bf16_f32 v63, v58, v59
	v_pk_mul_f32 v[58:59], v[54:55], v[54:55]
	v_cvt_pk_bf16_f32 v52, v52, v53
	v_cvt_pk_bf16_f32 v53, v54, v55
	v_add_f32_e32 v54, v56, v57
	v_add_f32_e32 v54, v58, v54
	v_add_f32_e32 v54, v59, v54
	v_add_f32_e32 v58, v72, v54
	v_permlane16_swap_b32_e32 v60, v62
	v_permlane16_swap_b32_e32 v61, v63
	v_pk_add_f32 v[48:49], v[48:49], v[66:67]
	v_pk_add_f32 v[50:51], v[50:51], v[68:69]
	v_pk_mul_f32 v[54:55], v[48:49], v[48:49]
	v_pk_mul_f32 v[56:57], v[50:51], v[50:51]
	v_add_f32_e32 v54, v54, v55
	v_add_f32_e32 v54, v56, v54
	v_add_f32_e32 v54, v57, v54
	v_add_f32_e32 v56, v58, v54
	ds_bpermute_b32 v57, v125, v56
	global_store_dwordx4 v[74:75], v[48:51], off offset:192
	v_cvt_pk_bf16_f32 v54, v48, v49
	v_cvt_pk_bf16_f32 v55, v50, v51
	s_nop 0
	v_permlane16_swap_b32_e32 v52, v54
	s_waitcnt lgkmcnt(0)
	v_add_f32_e32 v48, v56, v57
	ds_bpermute_b32 v49, v124, v48
	v_permlane16_swap_b32_e32 v53, v55
	global_store_dwordx4 v[70:71], v[60:63], off
	global_store_dwordx4 v[70:71], v[52:55], off offset:64
	s_and_saveexec_b64 s[6:7], vcc
	s_cbranch_execz .LBB0_446
	s_waitcnt lgkmcnt(0)
	v_add_f32_e32 v50, v48, v49
	v_lshl_add_u64 v[48:49], v[64:65], 2, s[12:13]
	global_atomic_add_f32 v[48:49], v50, off

; __device__ __forceinline__ u32x2 pk4(float a, float b, float c, float d) { return u32x2{cvtpk(a, b), cvtpk(c, d)}; }
; template <int EPI>
; __device__ __forceinline__ void gemm_tile(const Params& p, const u16* __restrict__ A, int lda, const u16* __restrict__ Bt, int ldb,
;                                           int K, int brow, int bcol, bool prefetched, int nbrow, int nbcol, char* shm) {
;     ...
;       for (int m = 0; m < 8; ++m) {
;         const int row = rbase + m * 16; float s = 0.f; u32x2 g[4];
;         const float* xr = (row < TP ? p.xp + (long)row * DM : p.xs + (long)(row - TP) * DM) + col0 + cq4;
; #pragma unroll
;         for (int n = 0; n < 4; ++n) {
;           float4 v = *(const float4*)(xr + n * 16);
;           v.x += acc[m][n][0]; v.y += acc[m][n][1]; v.z += acc[m][n][2]; v.w += acc[m][n][3];
;           s += v.x * v.x + v.y * v.y + v.z * v.z + v.w * v.w;
;           *(float4*)(p.out + (long)row * DM + col0 + cq4 + n * 16) = v; g[n] = pk4(v.x, v.y, v.z, v.w);
;         }
;         st_row64(xb + (long)row * DM + col0, fq, g[0], g[1], g[2], g[3]);
;         s = red4q(s); if (fq == 0) unsafeAtomicAdd(&ssq[row], s);
.LBB0_450:
	s_or_b64 exec, exec, s[6:7]
	v_lshl_add_u64 v[52:53], v[52:53], 0, v[128:129]
	v_lshl_add_u64 v[56:57], v[52:53], 0, v[172:173]
	v_lshl_add_u64 v[228:229], v[228:229], 0, s[98:99]
	global_load_dwordx4 v[152:155], v[228:229], off
	global_load_dwordx4 v[156:159], v[228:229], off offset:64
	global_load_dwordx4 v[160:163], v[228:229], off offset:128
	global_load_dwordx4 v[164:167], v[228:229], off offset:192
	v_readlane_b32 s72, v255, 0
	v_readlane_b32 s73, v255, 1
	v_mov_b32_e32 v117, v173
	v_mov_b32_e32 v119, v173
	v_lshl_add_u64 v[50:51], s[72:73], 0, v[50:51]
	v_lshl_add_u64 v[50:51], v[50:51], 0, v[128:129]
	v_lshl_add_u64 v[58:59], v[50:51], 0, v[172:173]
	v_readlane_b32 s74, v255, 2
	v_readlane_b32 s75, v255, 3
	v_readlane_b32 s76, v255, 4
	v_readlane_b32 s77, v255, 5
	v_readlane_b32 s78, v255, 6
	v_readlane_b32 s79, v255, 7
	v_readlane_b32 s80, v255, 8
	v_readlane_b32 s81, v255, 9
	v_readlane_b32 s82, v255, 10
	v_readlane_b32 s83, v255, 11
	v_readlane_b32 s84, v255, 12
	v_readlane_b32 s85, v255, 13
	v_readlane_b32 s86, v255, 14
	v_readlane_b32 s87, v255, 15
	s_waitcnt vmcnt(10)
	v_mov_b64_e32 v[52:53], v[168:169]
	v_mov_b64_e32 v[54:55], v[170:171]
	v_pk_add_f32 v[44:45], v[44:45], v[52:53]
	v_pk_add_f32 v[46:47], v[46:47], v[54:55]
	global_store_dwordx4 v[58:59], v[44:47], off
	v_mov_b64_e32 v[50:51], v[216:217]
	v_mov_b64_e32 v[52:53], v[218:219]
	v_pk_mul_f32 v[60:61], v[46:47], v[46:47]
	v_lshlrev_b64 v[54:55], 11, v[48:49]
	v_lshl_add_u64 v[54:55], v[120:121], 0, v[54:55]
	v_lshl_add_u64 v[54:55], v[54:55], 0, v[116:117]
	v_lshl_add_u64 v[54:55], v[54:55], 0, v[118:119]
	v_pk_add_f32 v[40:41], v[40:41], v[50:51]
	v_pk_add_f32 v[42:43], v[42:43], v[52:53]
	global_store_dwordx4 v[58:59], v[40:43], off offset:64
	v_mov_b64_e32 v[50:51], v[220:221]
	v_mov_b64_e32 v[52:53], v[222:223]
	v_pk_add_f32 v[36:37], v[36:37], v[50:51]
	v_pk_add_f32 v[38:39], v[38:39], v[52:53]
	global_store_dwordx4 v[58:59], v[36:39], off offset:128
	v_mov_b64_e32 v[50:51], v[224:225]
	v_mov_b64_e32 v[52:53], v[226:227]
	v_pk_mul_f32 v[56:57], v[44:45], v[44:45]
	v_cvt_pk_bf16_f32 v44, v44, v45
	v_cvt_pk_bf16_f32 v45, v46, v47
	v_add_f32_e32 v46, v56, v57
	v_add_f32_e32 v46, v60, v46
	v_pk_mul_f32 v[56:57], v[40:41], v[40:41]
	v_add_f32_e32 v62, v61, v46
	v_pk_mul_f32 v[60:61], v[42:43], v[42:43]
	v_cvt_pk_bf16_f32 v46, v40, v41
	v_add_f32_e32 v40, v56, v57
	v_add_f32_e32 v40, v60, v40
	v_add_f32_e32 v40, v61, v40
	v_add_f32_e32 v56, v62, v40
	v_pk_mul_f32 v[40:41], v[36:37], v[36:37]
	v_cvt_pk_bf16_f32 v47, v42, v43
	v_pk_mul_f32 v[42:43], v[38:39], v[38:39]
	v_cvt_pk_bf16_f32 v36, v36, v37
	v_cvt_pk_bf16_f32 v37, v38, v39
	v_add_f32_e32 v38, v40, v41
	v_add_f32_e32 v38, v42, v38
	v_add_f32_e32 v38, v43, v38
	v_add_f32_e32 v42, v56, v38
	v_permlane16_swap_b32_e32 v44, v46
	v_permlane16_swap_b32_e32 v45, v47
	v_pk_add_f32 v[32:33], v[32:33], v[50:51]
	v_pk_add_f32 v[34:35], v[34:35], v[52:53]
	v_pk_mul_f32 v[38:39], v[32:33], v[32:33]
	v_pk_mul_f32 v[40:41], v[34:35], v[34:35]
	v_add_f32_e32 v38, v38, v39
	v_add_f32_e32 v38, v40, v38
	v_add_f32_e32 v38, v41, v38
	v_add_f32_e32 v40, v42, v38
	ds_bpermute_b32 v41, v125, v40
	global_store_dwordx4 v[58:59], v[32:35], off offset:192
	v_cvt_pk_bf16_f32 v38, v32, v33
	v_cvt_pk_bf16_f32 v39, v34, v35
	s_nop 0
	v_permlane16_swap_b32_e32 v36, v38
	s_waitcnt lgkmcnt(0)
	v_add_f32_e32 v32, v40, v41
	ds_bpermute_b32 v33, v124, v32
	v_permlane16_swap_b32_e32 v37, v39
	global_store_dwordx4 v[54:55], v[44:47], off
	global_store_dwordx4 v[54:55], v[36:39], off offset:64
	s_and_saveexec_b64 s[6:7], vcc
	s_cbranch_execz .LBB0_452
	s_waitcnt lgkmcnt(0)
	v_add_f32_e32 v34, v32, v33
	v_lshl_add_u64 v[32:33], v[48:49], 2, s[12:13]
	global_atomic_add_f32 v[32:33], v34, off

; __device__ __forceinline__ u32x2 pk4(float a, float b, float c, float d) { return u32x2{cvtpk(a, b), cvtpk(c, d)}; }
; template <int EPI>
; __device__ __forceinline__ void gemm_tile(const Params& p, const u16* __restrict__ A, int lda, const u16* __restrict__ Bt, int ldb,
;                                           int K, int brow, int bcol, bool prefetched, int nbrow, int nbcol, char* shm) {
;     ...
;       for (int m = 0; m < 8; ++m) {
;         const int row = rbase + m * 16; float s = 0.f; u32x2 g[4];
;         const float* xr = (row < TP ? p.xp + (long)row * DM : p.xs + (long)(row - TP) * DM) + col0 + cq4;
; #pragma unroll
;         for (int n = 0; n < 4; ++n) {
;           float4 v = *(const float4*)(xr + n * 16);
;           v.x += acc[m][n][0]; v.y += acc[m][n][1]; v.z += acc[m][n][2]; v.w += acc[m][n][3];
;           s += v.x * v.x + v.y * v.y + v.z * v.z + v.w * v.w;
;           *(float4*)(p.out + (long)row * DM + col0 + cq4 + n * 16) = v; g[n] = pk4(v.x, v.y, v.z, v.w);
;         }
;         st_row64(xb + (long)row * DM + col0, fq, g[0], g[1], g[2], g[3]);
;         s = red4q(s); if (fq == 0) unsafeAtomicAdd(&ssq[row], s);
.LBB0_456:
	s_or_b64 exec, exec, s[6:7]
	v_lshl_add_u64 v[36:37], v[36:37], 0, v[128:129]
	v_lshl_add_u64 v[40:41], v[36:37], 0, v[172:173]
	v_lshl_add_u64 v[228:229], v[228:229], 0, s[98:99]
	global_load_dwordx4 v[168:171], v[228:229], off
	global_load_dwordx4 v[216:219], v[228:229], off offset:64
	global_load_dwordx4 v[220:223], v[228:229], off offset:128
	global_load_dwordx4 v[224:227], v[228:229], off offset:192
	v_readlane_b32 s72, v255, 0
	v_readlane_b32 s73, v255, 1
	v_mov_b32_e32 v117, v173
	v_mov_b32_e32 v119, v173
	v_lshl_add_u64 v[34:35], s[72:73], 0, v[34:35]
	v_lshl_add_u64 v[34:35], v[34:35], 0, v[128:129]
	v_lshl_add_u64 v[42:43], v[34:35], 0, v[172:173]
	v_readlane_b32 s74, v255, 2
	v_readlane_b32 s75, v255, 3
	v_readlane_b32 s76, v255, 4
	v_readlane_b32 s77, v255, 5
	v_readlane_b32 s78, v255, 6
	v_readlane_b32 s79, v255, 7
	v_readlane_b32 s80, v255, 8
	v_readlane_b32 s81, v255, 9
	v_readlane_b32 s82, v255, 10
	v_readlane_b32 s83, v255, 11
	v_readlane_b32 s84, v255, 12
	v_readlane_b32 s85, v255, 13
	v_readlane_b32 s86, v255, 14
	v_readlane_b32 s87, v255, 15
	s_waitcnt vmcnt(10)
	v_mov_b64_e32 v[36:37], v[152:153]
	v_mov_b64_e32 v[38:39], v[154:155]
	v_pk_add_f32 v[28:29], v[28:29], v[36:37]
	v_pk_add_f32 v[30:31], v[30:31], v[38:39]
	global_store_dwordx4 v[42:43], v[28:31], off
	v_mov_b64_e32 v[34:35], v[156:157]
	v_mov_b64_e32 v[36:37], v[158:159]
	v_pk_mul_f32 v[44:45], v[30:31], v[30:31]
	v_lshlrev_b64 v[38:39], 11, v[32:33]
	v_lshl_add_u64 v[38:39], v[120:121], 0, v[38:39]
	v_lshl_add_u64 v[38:39], v[38:39], 0, v[116:117]
	v_lshl_add_u64 v[38:39], v[38:39], 0, v[118:119]
	v_pk_add_f32 v[24:25], v[24:25], v[34:35]
	v_pk_add_f32 v[26:27], v[26:27], v[36:37]
	global_store_dwordx4 v[42:43], v[24:27], off offset:64
	v_mov_b64_e32 v[34:35], v[160:161]
	v_mov_b64_e32 v[36:37], v[162:163]
	v_pk_add_f32 v[20:21], v[20:21], v[34:35]
	v_pk_add_f32 v[22:23], v[22:23], v[36:37]
	global_store_dwordx4 v[42:43], v[20:23], off offset:128
	v_mov_b64_e32 v[34:35], v[164:165]
	v_mov_b64_e32 v[36:37], v[166:167]
	v_pk_mul_f32 v[40:41], v[28:29], v[28:29]
	v_cvt_pk_bf16_f32 v28, v28, v29
	v_cvt_pk_bf16_f32 v29, v30, v31
	v_add_f32_e32 v30, v40, v41
	v_add_f32_e32 v30, v44, v30
	v_pk_mul_f32 v[40:41], v[24:25], v[24:25]
	v_add_f32_e32 v46, v45, v30
	v_pk_mul_f32 v[44:45], v[26:27], v[26:27]
	v_cvt_pk_bf16_f32 v30, v24, v25
	v_add_f32_e32 v24, v40, v41
	v_add_f32_e32 v24, v44, v24
	v_add_f32_e32 v24, v45, v24
	v_add_f32_e32 v40, v46, v24
	v_pk_mul_f32 v[24:25], v[20:21], v[20:21]
	v_cvt_pk_bf16_f32 v31, v26, v27
	v_pk_mul_f32 v[26:27], v[22:23], v[22:23]
	v_cvt_pk_bf16_f32 v20, v20, v21
	v_cvt_pk_bf16_f32 v21, v22, v23
	v_add_f32_e32 v22, v24, v25
	v_add_f32_e32 v22, v26, v22
	v_add_f32_e32 v22, v27, v22
	v_add_f32_e32 v26, v40, v22
	v_permlane16_swap_b32_e32 v28, v30
	v_permlane16_swap_b32_e32 v29, v31
	v_pk_add_f32 v[16:17], v[16:17], v[34:35]
	v_pk_add_f32 v[18:19], v[18:19], v[36:37]
	v_pk_mul_f32 v[22:23], v[16:17], v[16:17]
	v_pk_mul_f32 v[24:25], v[18:19], v[18:19]
	v_add_f32_e32 v22, v22, v23
	v_add_f32_e32 v22, v24, v22
	v_add_f32_e32 v22, v25, v22
	v_add_f32_e32 v24, v26, v22
	ds_bpermute_b32 v25, v125, v24
	global_store_dwordx4 v[42:43], v[16:19], off offset:192
	v_cvt_pk_bf16_f32 v22, v16, v17
	v_cvt_pk_bf16_f32 v23, v18, v19
	s_nop 0
	v_permlane16_swap_b32_e32 v20, v22
	s_waitcnt lgkmcnt(0)
	v_add_f32_e32 v16, v24, v25
	ds_bpermute_b32 v17, v124, v16
	v_permlane16_swap_b32_e32 v21, v23
	global_store_dwordx4 v[38:39], v[28:31], off
	global_store_dwordx4 v[38:39], v[20:23], off offset:64
	s_and_saveexec_b64 s[6:7], vcc
	s_cbranch_execz .LBB0_458
	s_waitcnt lgkmcnt(0)
	v_add_f32_e32 v18, v16, v17
	v_lshl_add_u64 v[16:17], v[32:33], 2, s[12:13]
	global_atomic_add_f32 v[16:17], v18, off

; __device__ __forceinline__ u32x2 pk4(float a, float b, float c, float d) { return u32x2{cvtpk(a, b), cvtpk(c, d)}; }
; template <int EPI>
; __device__ __forceinline__ void gemm_tile(const Params& p, const u16* __restrict__ A, int lda, const u16* __restrict__ Bt, int ldb,
;                                           int K, int brow, int bcol, bool prefetched, int nbrow, int nbcol, char* shm) {
;     ...
;       for (int m = 0; m < 8; ++m) {
;         const int row = rbase + m * 16; float s = 0.f; u32x2 g[4];
;         const float* xr = (row < TP ? p.xp + (long)row * DM : p.xs + (long)(row - TP) * DM) + col0 + cq4;
; #pragma unroll
;         for (int n = 0; n < 4; ++n) {
;           float4 v = *(const float4*)(xr + n * 16);
;           v.x += acc[m][n][0]; v.y += acc[m][n][1]; v.z += acc[m][n][2]; v.w += acc[m][n][3];
;           s += v.x * v.x + v.y * v.y + v.z * v.z + v.w * v.w;
;           *(float4*)(p.out + (long)row * DM + col0 + cq4 + n * 16) = v; g[n] = pk4(v.x, v.y, v.z, v.w);
;         }
;         st_row64(xb + (long)row * DM + col0, fq, g[0], g[1], g[2], g[3]);
;         s = red4q(s); if (fq == 0) unsafeAtomicAdd(&ssq[row], s);
.LBB0_462:
	s_or_b64 exec, exec, s[6:7]
	v_lshl_add_u64 v[20:21], v[20:21], 0, v[128:129]
	v_lshl_add_u64 v[24:25], v[20:21], 0, v[172:173]
	v_readlane_b32 s72, v255, 0
	v_readlane_b32 s73, v255, 1
	v_mov_b32_e32 v117, v173
	v_mov_b32_e32 v119, v173
	v_lshl_add_u64 v[18:19], s[72:73], 0, v[18:19]
	v_lshl_add_u64 v[18:19], v[18:19], 0, v[128:129]
	v_lshl_add_u64 v[26:27], v[18:19], 0, v[172:173]
	v_readlane_b32 s74, v255, 2
	v_readlane_b32 s75, v255, 3
	v_readlane_b32 s76, v255, 4
	v_readlane_b32 s77, v255, 5
	v_readlane_b32 s78, v255, 6
	v_readlane_b32 s79, v255, 7
	v_readlane_b32 s80, v255, 8
	v_readlane_b32 s81, v255, 9
	v_readlane_b32 s82, v255, 10
	v_readlane_b32 s83, v255, 11
	v_readlane_b32 s84, v255, 12
	v_readlane_b32 s85, v255, 13
	v_readlane_b32 s86, v255, 14
	v_readlane_b32 s87, v255, 15
	s_waitcnt vmcnt(6)
	v_mov_b64_e32 v[20:21], v[168:169]
	v_mov_b64_e32 v[22:23], v[170:171]
	v_pk_add_f32 v[12:13], v[12:13], v[20:21]
	v_pk_add_f32 v[14:15], v[14:15], v[22:23]
	global_store_dwordx4 v[26:27], v[12:15], off
	v_mov_b64_e32 v[18:19], v[216:217]
	v_mov_b64_e32 v[20:21], v[218:219]
	v_pk_mul_f32 v[28:29], v[14:15], v[14:15]
	v_lshlrev_b64 v[22:23], 11, v[16:17]
	v_lshl_add_u64 v[22:23], v[120:121], 0, v[22:23]
	v_lshl_add_u64 v[22:23], v[22:23], 0, v[116:117]
	v_lshl_add_u64 v[22:23], v[22:23], 0, v[118:119]
	v_pk_add_f32 v[8:9], v[8:9], v[18:19]
	v_pk_add_f32 v[10:11], v[10:11], v[20:21]
	global_store_dwordx4 v[26:27], v[8:11], off offset:64
	v_mov_b64_e32 v[18:19], v[220:221]
	v_mov_b64_e32 v[20:21], v[222:223]
	v_pk_add_f32 v[4:5], v[4:5], v[18:19]
	v_pk_add_f32 v[6:7], v[6:7], v[20:21]
	global_store_dwordx4 v[26:27], v[4:7], off offset:128
	v_mov_b64_e32 v[18:19], v[224:225]
	v_mov_b64_e32 v[20:21], v[226:227]
	v_pk_mul_f32 v[24:25], v[12:13], v[12:13]
	v_cvt_pk_bf16_f32 v12, v12, v13
	v_cvt_pk_bf16_f32 v13, v14, v15
	v_add_f32_e32 v14, v24, v25
	v_add_f32_e32 v14, v28, v14
	v_pk_mul_f32 v[24:25], v[8:9], v[8:9]
	v_add_f32_e32 v30, v29, v14
	v_pk_mul_f32 v[28:29], v[10:11], v[10:11]
	v_cvt_pk_bf16_f32 v14, v8, v9
	v_add_f32_e32 v8, v24, v25
	v_add_f32_e32 v8, v28, v8
	v_add_f32_e32 v8, v29, v8
	v_add_f32_e32 v24, v30, v8
	v_pk_mul_f32 v[8:9], v[4:5], v[4:5]
	v_cvt_pk_bf16_f32 v15, v10, v11
	v_pk_mul_f32 v[10:11], v[6:7], v[6:7]
	v_cvt_pk_bf16_f32 v4, v4, v5
	v_cvt_pk_bf16_f32 v5, v6, v7
	v_add_f32_e32 v6, v8, v9
	v_add_f32_e32 v6, v10, v6
	v_add_f32_e32 v6, v11, v6
	v_add_f32_e32 v10, v24, v6
	v_permlane16_swap_b32_e32 v12, v14
	v_permlane16_swap_b32_e32 v13, v15
	v_pk_add_f32 v[0:1], v[0:1], v[18:19]
	v_pk_add_f32 v[2:3], v[2:3], v[20:21]
	v_pk_mul_f32 v[6:7], v[0:1], v[0:1]
	v_pk_mul_f32 v[8:9], v[2:3], v[2:3]
	v_add_f32_e32 v6, v6, v7
	v_add_f32_e32 v6, v8, v6
	v_add_f32_e32 v6, v9, v6
	v_add_f32_e32 v8, v10, v6
	ds_bpermute_b32 v9, v125, v8
	global_store_dwordx4 v[26:27], v[0:3], off offset:192
	v_cvt_pk_bf16_f32 v6, v0, v1
	v_cvt_pk_bf16_f32 v7, v2, v3
	s_nop 0
	v_permlane16_swap_b32_e32 v4, v6
	s_waitcnt lgkmcnt(0)
	v_add_f32_e32 v0, v8, v9
	ds_bpermute_b32 v1, v124, v0
	v_permlane16_swap_b32_e32 v5, v7
	global_store_dwordx4 v[22:23], v[12:15], off
	global_store_dwordx4 v[22:23], v[4:7], off offset:64
	s_and_saveexec_b64 s[6:7], vcc
	s_cbranch_execz .LBB0_383
	s_waitcnt lgkmcnt(0)
	v_add_f32_e32 v2, v0, v1
	v_lshl_add_u64 v[0:1], v[16:17], 2, s[12:13]
	global_atomic_add_f32 v[0:1], v2, off
	s_branch .LBB0_383
